# linear-attention item epilogue: per-row sums via DPP row rotations (8,4,2,1) instead of ds_bpermute butterflies
# speedup vs baseline: 1.0284x; 1.0033x over previous
.LBB0_186:
	v_mul_f32_e32 v95, 0x3fb8aa3b, v36
	v_mul_f32_e32 v36, 0xbfb8aa3b, v36
	v_exp_f32_e32 v95, v95
	v_exp_f32_e32 v36, v36
	s_waitcnt vmcnt(55)
	v_lshlrev_b32_e32 v93, 16, v93
	s_waitcnt vmcnt(51)
	v_lshlrev_b32_e32 v94, 16, v94
	s_mul_i32 s6, s35, 0x48
	v_mul_f32_e32 v96, v95, v93
	v_or_b32_e32 v97, s6, v60
	v_mul_f32_e32 v93, v36, v93
	v_mul_f32_e32 v36, v36, v94
	v_lshlrev_b32_e32 v97, 1, v97
	v_cvt_pk_bf16_f32 v36, v36, s0
	ds_write_b16 v97, v36 offset:27648
	v_lshlrev_b32_e32 v36, 16, v91
	v_mul_f32_e32 v91, 0x3fb8aa3b, v37
	v_mul_f32_e32 v37, 0xbfb8aa3b, v37
	v_exp_f32_e32 v91, v91
	v_exp_f32_e32 v37, v37
	v_cvt_pk_bf16_f32 v93, v93, s0
	ds_write_b16 v97, v93 offset:9216
	v_mul_f32_e32 v93, v95, v94
	v_cvt_pk_bf16_f32 v93, v93, s0
	ds_write_b16 v97, v93 offset:18432
	v_mul_f32_e32 v93, v91, v36
	v_mul_f32_e32 v36, v37, v36
	v_cvt_pk_bf16_f32 v96, v96, s0
	s_waitcnt vmcnt(50)
	v_lshlrev_b32_e32 v92, 16, v92
	v_add_lshl_u32 v94, s6, v60, 1
	v_cvt_pk_bf16_f32 v36, v36, s0
	ds_write_b16 v97, v96
	ds_write_b16 v94, v36 offset:9360
	v_mul_f32_e32 v36, v91, v92
	v_cvt_pk_bf16_f32 v36, v36, s0
	ds_write_b16 v94, v36 offset:18576
	v_mul_f32_e32 v36, v37, v92
	v_mul_f32_e32 v37, 0x3fb8aa3b, v34
	v_mul_f32_e32 v34, 0xbfb8aa3b, v34
	v_exp_f32_e32 v37, v37
	v_exp_f32_e32 v34, v34
	v_cvt_pk_bf16_f32 v36, v36, s0
	ds_write_b16 v94, v36 offset:27792
	v_lshlrev_b32_e32 v36, 16, v89
	s_waitcnt vmcnt(49)
	v_lshlrev_b32_e32 v89, 16, v90
	v_mul_f32_e32 v90, v37, v36
	v_mul_f32_e32 v36, v34, v36
	v_cvt_pk_bf16_f32 v36, v36, s0
	ds_write_b16 v94, v36 offset:9504
	v_mul_f32_e32 v36, v37, v89
	v_cvt_pk_bf16_f32 v36, v36, s0
	ds_write_b16 v94, v36 offset:18720
	v_mul_f32_e32 v36, 0x3fb8aa3b, v35
	v_mul_f32_e32 v35, 0xbfb8aa3b, v35
	v_exp_f32_e32 v36, v36
	v_exp_f32_e32 v35, v35
	v_mul_f32_e32 v34, v34, v89
	v_cvt_pk_bf16_f32 v34, v34, s0
	ds_write_b16 v94, v34 offset:27936
	v_lshlrev_b32_e32 v34, 16, v87
	v_mul_f32_e32 v87, v36, v34
	v_mul_f32_e32 v34, v35, v34
	s_waitcnt vmcnt(48)
	v_lshlrev_b32_e32 v37, 16, v88
	v_cvt_pk_bf16_f32 v34, v34, s0
	ds_write_b16 v94, v34 offset:9648
	v_mul_f32_e32 v34, v36, v37
	v_cvt_pk_bf16_f32 v34, v34, s0
	ds_write_b16 v94, v34 offset:18864
	v_mul_f32_e32 v34, v35, v37
	v_mul_f32_e32 v35, 0x3fb8aa3b, v32
	v_mul_f32_e32 v32, 0xbfb8aa3b, v32
	v_exp_f32_e32 v35, v35
	v_exp_f32_e32 v32, v32
	v_cvt_pk_bf16_f32 v34, v34, s0
	ds_write_b16 v94, v34 offset:28080
	s_waitcnt vmcnt(47)
	v_lshlrev_b32_e32 v34, 16, v85
	v_mul_f32_e32 v37, v35, v34
	v_mul_f32_e32 v34, v32, v34
	s_waitcnt vmcnt(44)
	v_lshlrev_b32_e32 v36, 16, v86
	v_cvt_pk_bf16_f32 v34, v34, s0
	ds_write_b16 v94, v34 offset:9792
	v_mul_f32_e32 v34, v35, v36
	v_cvt_pk_bf16_f32 v34, v34, s0
	ds_write_b16 v94, v34 offset:19008
	v_mul_f32_e32 v34, 0x3fb8aa3b, v33
	v_mul_f32_e32 v33, 0xbfb8aa3b, v33
	v_exp_f32_e32 v34, v34
	v_exp_f32_e32 v33, v33
	v_mul_f32_e32 v32, v32, v36
	v_cvt_pk_bf16_f32 v32, v32, s0
	ds_write_b16 v94, v32 offset:28224
	v_lshlrev_b32_e32 v32, 16, v83
	v_mul_f32_e32 v36, v34, v32
	v_mul_f32_e32 v32, v33, v32
	s_waitcnt vmcnt(43)
	v_lshlrev_b32_e32 v35, 16, v84
	v_cvt_pk_bf16_f32 v32, v32, s0
	ds_write_b16 v94, v32 offset:9936
	v_mul_f32_e32 v32, v34, v35
	v_cvt_pk_bf16_f32 v32, v32, s0
	ds_write_b16 v94, v32 offset:19152
	v_mul_f32_e32 v32, v33, v35
	v_mul_f32_e32 v33, 0x3fb8aa3b, v30
	v_mul_f32_e32 v30, 0xbfb8aa3b, v30
	v_exp_f32_e32 v33, v33
	v_exp_f32_e32 v30, v30
	v_cvt_pk_bf16_f32 v32, v32, s0
	ds_write_b16 v94, v32 offset:28368
	v_lshlrev_b32_e32 v32, 16, v80
	v_mul_f32_e32 v35, v33, v32
	v_mul_f32_e32 v32, v30, v32
	s_waitcnt vmcnt(42)
	v_lshlrev_b32_e32 v34, 16, v79
	v_cvt_pk_bf16_f32 v32, v32, s0
	ds_write_b16 v94, v32 offset:10080
	v_mul_f32_e32 v32, v33, v34
	v_cvt_pk_bf16_f32 v32, v32, s0
	ds_write_b16 v94, v32 offset:19296
	v_mul_f32_e32 v32, 0x3fb8aa3b, v31
	v_mul_f32_e32 v31, 0xbfb8aa3b, v31
	v_exp_f32_e32 v32, v32
	v_exp_f32_e32 v31, v31
	v_mul_f32_e32 v30, v30, v34
	v_cvt_pk_bf16_f32 v30, v30, s0
	ds_write_b16 v94, v30 offset:28512
	s_waitcnt vmcnt(39)
	v_lshlrev_b32_e32 v30, 16, v82
	v_mul_f32_e32 v34, v32, v30
	v_mul_f32_e32 v30, v31, v30
	s_waitcnt vmcnt(37)
	v_lshlrev_b32_e32 v33, 16, v81
	v_cvt_pk_bf16_f32 v30, v30, s0
	ds_write_b16 v94, v30 offset:10224
	v_mul_f32_e32 v30, v32, v33
	v_cvt_pk_bf16_f32 v30, v30, s0
	ds_write_b16 v94, v30 offset:19440
	v_mul_f32_e32 v30, v31, v33
	v_mul_f32_e32 v31, 0x3fb8aa3b, v28
	v_mul_f32_e32 v28, 0xbfb8aa3b, v28
	v_exp_f32_e32 v31, v31
	v_exp_f32_e32 v28, v28
	v_cvt_pk_bf16_f32 v30, v30, s0
	ds_write_b16 v94, v30 offset:28656
	v_lshlrev_b32_e32 v30, 16, v78
	v_mul_f32_e32 v33, v31, v30
	v_mul_f32_e32 v30, v28, v30
	v_lshlrev_b32_e32 v32, 16, v77
	v_cvt_pk_bf16_f32 v30, v30, s0
	ds_write_b16 v94, v30 offset:10368
	v_mul_f32_e32 v30, v31, v32
	v_cvt_pk_bf16_f32 v30, v30, s0
	ds_write_b16 v94, v30 offset:19584
	v_mul_f32_e32 v30, 0x3fb8aa3b, v29
	v_mul_f32_e32 v29, 0xbfb8aa3b, v29
	v_exp_f32_e32 v30, v30
	v_exp_f32_e32 v29, v29
	v_mul_f32_e32 v28, v28, v32
	v_cvt_pk_bf16_f32 v28, v28, s0
	ds_write_b16 v94, v28 offset:28800
	v_lshlrev_b32_e32 v28, 16, v76
	v_mul_f32_e32 v32, v30, v28
	v_mul_f32_e32 v28, v29, v28
	s_waitcnt vmcnt(36)
	v_lshlrev_b32_e32 v31, 16, v75
	v_cvt_pk_bf16_f32 v28, v28, s0
	ds_write_b16 v94, v28 offset:10512
	v_mul_f32_e32 v28, v30, v31
	v_cvt_pk_bf16_f32 v28, v28, s0
	ds_write_b16 v94, v28 offset:19728
	v_mul_f32_e32 v28, v29, v31
	v_mul_f32_e32 v29, 0x3fb8aa3b, v26
	v_mul_f32_e32 v26, 0xbfb8aa3b, v26
	v_exp_f32_e32 v29, v29
	v_exp_f32_e32 v26, v26
	v_cvt_pk_bf16_f32 v28, v28, s0
	ds_write_b16 v94, v28 offset:28944
	s_waitcnt vmcnt(35)
	v_lshlrev_b32_e32 v28, 16, v73
	v_mul_f32_e32 v31, v29, v28
	v_mul_f32_e32 v28, v26, v28
	s_waitcnt vmcnt(32)
	v_lshlrev_b32_e32 v30, 16, v74
	v_cvt_pk_bf16_f32 v28, v28, s0
	ds_write_b16 v94, v28 offset:10656
	v_mul_f32_e32 v28, v29, v30
	v_cvt_pk_bf16_f32 v28, v28, s0
	ds_write_b16 v94, v28 offset:19872
	v_mul_f32_e32 v28, 0x3fb8aa3b, v27
	v_mul_f32_e32 v27, 0xbfb8aa3b, v27
	v_exp_f32_e32 v28, v28
	v_exp_f32_e32 v27, v27
	v_mul_f32_e32 v26, v26, v30
	v_cvt_pk_bf16_f32 v26, v26, s0
	ds_write_b16 v94, v26 offset:29088
	v_lshlrev_b32_e32 v26, 16, v71
	v_mul_f32_e32 v30, v28, v26
	v_mul_f32_e32 v26, v27, v26
	s_waitcnt vmcnt(31)
	v_lshlrev_b32_e32 v29, 16, v72
	v_cvt_pk_bf16_f32 v26, v26, s0
	ds_write_b16 v94, v26 offset:10800
	v_mul_f32_e32 v26, v28, v29
	v_cvt_pk_bf16_f32 v26, v26, s0
	ds_write_b16 v94, v26 offset:20016
	v_mul_f32_e32 v26, v27, v29
	v_mul_f32_e32 v27, 0x3fb8aa3b, v24
	v_mul_f32_e32 v24, 0xbfb8aa3b, v24
	v_exp_f32_e32 v27, v27
	v_exp_f32_e32 v24, v24
	v_cvt_pk_bf16_f32 v26, v26, s0
	ds_write_b16 v94, v26 offset:29232
	v_lshlrev_b32_e32 v26, 16, v70
	v_mul_f32_e32 v29, v27, v26
	v_mul_f32_e32 v26, v24, v26
	s_waitcnt vmcnt(30)
	v_lshlrev_b32_e32 v28, 16, v69
	v_cvt_pk_bf16_f32 v26, v26, s0
	ds_write_b16 v94, v26 offset:10944
	v_mul_f32_e32 v26, v27, v28
	v_cvt_pk_bf16_f32 v26, v26, s0
	ds_write_b16 v94, v26 offset:20160
	v_mul_f32_e32 v26, 0x3fb8aa3b, v25
	v_mul_f32_e32 v25, 0xbfb8aa3b, v25
	v_exp_f32_e32 v26, v26
	v_exp_f32_e32 v25, v25
	v_mul_f32_e32 v24, v24, v28
	v_cvt_pk_bf16_f32 v24, v24, s0
	ds_write_b16 v94, v24 offset:29376
	s_waitcnt vmcnt(29)
	v_lshlrev_b32_e32 v24, 16, v67
	v_mul_f32_e32 v28, v26, v24
	v_mul_f32_e32 v24, v25, v24
	s_waitcnt vmcnt(26)
	v_lshlrev_b32_e32 v27, 16, v68
	v_cvt_pk_bf16_f32 v24, v24, s0
	ds_write_b16 v94, v24 offset:11088
	v_mul_f32_e32 v24, v26, v27
	v_cvt_pk_bf16_f32 v24, v24, s0
	ds_write_b16 v94, v24 offset:20304
	v_mul_f32_e32 v24, v25, v27
	v_mul_f32_e32 v25, 0x3fb8aa3b, v22
	v_mul_f32_e32 v22, 0xbfb8aa3b, v22
	v_exp_f32_e32 v25, v25
	v_exp_f32_e32 v22, v22
	v_cvt_pk_bf16_f32 v24, v24, s0
	ds_write_b16 v94, v24 offset:29520
	v_lshlrev_b32_e32 v24, 16, v64
	v_mul_f32_e32 v27, v25, v24
	v_mul_f32_e32 v24, v22, v24
	s_waitcnt vmcnt(25)
	v_lshlrev_b32_e32 v26, 16, v65
	v_cvt_pk_bf16_f32 v24, v24, s0
	ds_write_b16 v94, v24 offset:11232
	v_mul_f32_e32 v24, v25, v26
	v_cvt_pk_bf16_f32 v24, v24, s0
	ds_write_b16 v94, v24 offset:20448
	v_mul_f32_e32 v24, 0x3fb8aa3b, v23
	v_mul_f32_e32 v23, 0xbfb8aa3b, v23
	v_exp_f32_e32 v24, v24
	v_exp_f32_e32 v23, v23
	v_mul_f32_e32 v22, v22, v26
	v_cvt_pk_bf16_f32 v22, v22, s0
	ds_write_b16 v94, v22 offset:29664
	s_or_b32 s6, s36, 15
	v_lshlrev_b32_e32 v22, 16, v63
	v_cvt_pk_bf16_f32 v27, v27, s0
	v_mul_f32_e32 v26, v24, v22
	s_mulk_i32 s6, 0x48
	v_mul_f32_e32 v22, v23, v22
	v_cvt_pk_bf16_f32 v93, v93, s0
	v_cvt_pk_bf16_f32 v90, v90, s0
	v_cvt_pk_bf16_f32 v87, v87, s0
	v_cvt_pk_bf16_f32 v37, v37, s0
	v_cvt_pk_bf16_f32 v36, v36, s0
	v_cvt_pk_bf16_f32 v35, v35, s0
	v_cvt_pk_bf16_f32 v34, v34, s0
	v_cvt_pk_bf16_f32 v33, v33, s0
	v_cvt_pk_bf16_f32 v32, v32, s0
	v_cvt_pk_bf16_f32 v31, v31, s0
	v_cvt_pk_bf16_f32 v30, v30, s0
	v_cvt_pk_bf16_f32 v29, v29, s0
	v_cvt_pk_bf16_f32 v28, v28, s0
	ds_write_b16 v94, v27 offset:2016
	s_waitcnt vmcnt(24)
	v_lshlrev_b32_e32 v25, 16, v62
	v_add_lshl_u32 v27, s6, v60, 1
	v_cvt_pk_bf16_f32 v22, v22, s0
	ds_write_b16 v94, v93 offset:144
	ds_write_b16 v94, v90 offset:288
	ds_write_b16 v94, v87 offset:432
	ds_write_b16 v94, v37 offset:576
	ds_write_b16 v94, v36 offset:720
	ds_write_b16 v94, v35 offset:864
	ds_write_b16 v94, v34 offset:1008
	ds_write_b16 v94, v33 offset:1152
	ds_write_b16 v94, v32 offset:1296
	ds_write_b16 v94, v31 offset:1440
	ds_write_b16 v94, v30 offset:1584
	ds_write_b16 v94, v29 offset:1728
	ds_write_b16 v94, v28 offset:1872
	ds_write_b16 v27, v22 offset:9216
	v_mul_f32_e32 v22, v24, v25
	v_cvt_pk_bf16_f32 v22, v22, s0
	ds_write_b16 v27, v22 offset:18432
	v_mul_f32_e32 v22, v23, v25
	v_mul_lo_u32 v20, v20, s98
	v_cvt_pk_bf16_f32 v26, v26, s0
	v_cvt_pk_bf16_f32 v22, v22, s0
	v_lshl_add_u32 v20, v61, 1, v20
	ds_write_b16 v27, v26
	ds_write_b16 v27, v22 offset:27648
	s_waitcnt vmcnt(23)
	ds_write_b128 v20, v[2:5] offset:36864
	s_waitcnt vmcnt(22)
	ds_write_b128 v20, v[6:9] offset:46080
	s_waitcnt vmcnt(21)
	ds_write_b128 v20, v[10:13] offset:41472
	s_waitcnt vmcnt(20)
	ds_write_b128 v20, v[14:17] offset:50688
	v_lshlrev_b32_e32 v6, 4, v66
	v_mul_u32_u24_e32 v2, 0x48, v54
	v_lshl_add_u32 v20, v2, 1, v6
	s_waitcnt lgkmcnt(0)
	s_barrier
	ds_read_b128 v[2:5], v20 offset:27648
	v_or_b32_e32 v68, s35, v54
	v_mad_u64_u32 v[34:35], s[6:7], v68, s98, v[6:7]
	ds_read_b128 v[6:9], v34
	ds_read_b128 v[10:13], v20 offset:18432
	ds_read_b128 v[22:25], v34 offset:9216
	ds_read_b128 v[26:29], v20 offset:27712
	ds_read_b128 v[14:17], v34 offset:64
	s_waitcnt lgkmcnt(4)
	v_mfma_f32_16x16x32_bf16 v[2:5], v[2:5], v[6:9], 0
	ds_read_b128 v[30:33], v20 offset:18496
	ds_read_b128 v[34:37], v34 offset:9280
	ds_read_b128 v[60:63], v20 offset:30016
	ds_read_b128 v[64:67], v20 offset:20800
	s_waitcnt lgkmcnt(6)
	v_mfma_f32_16x16x32_bf16 v[10:13], v[10:13], v[22:25], 0
	v_cmp_lt_i32_e32 vcc, v68, v59
	s_add_i32 s35, s34, 0x180
	s_and_b64 s[6:7], s[38:39], exec
	s_waitcnt lgkmcnt(4)
	v_mfma_f32_16x16x32_bf16 v[2:5], v[26:29], v[14:17], v[2:5]
	ds_read_b128 v[26:29], v20 offset:29952
	s_cselect_b32 s6, s34, s35
	s_mov_b32 s34, 0x358637bd
	s_waitcnt lgkmcnt(3)
	v_mfma_f32_16x16x32_bf16 v[10:13], v[30:33], v[34:37], v[10:13]
	ds_read_b128 v[30:33], v20 offset:20736
	s_lshr_b32 s6, s6, 5
	s_lshl_b32 s6, s6, 20
	s_add_u32 s6, s48, s6
	s_waitcnt lgkmcnt(1)
	v_mfma_f32_16x16x32_bf16 v[26:29], v[26:29], v[6:9], 0
	s_addc_u32 s7, s49, 0
	s_nop 1
	v_cndmask_b32_e32 v69, v2, v10, vcc
	v_cmp_gt_i32_e32 vcc, v68, v59
	v_or_b32_e32 v2, 2, v59
	s_waitcnt lgkmcnt(0)
	v_mfma_f32_16x16x32_bf16 v[30:33], v[30:33], v[22:25], 0
	v_cndmask_b32_e32 v70, v11, v3, vcc
	v_cmp_lt_i32_e32 vcc, v68, v2
	v_or_b32_e32 v2, 3, v59
	v_mfma_f32_16x16x32_bf16 v[26:29], v[60:63], v[14:17], v[26:29]
	v_cndmask_b32_e32 v71, v4, v12, vcc
	v_cmp_lt_i32_e32 vcc, v68, v2
	ds_read_b128 v[60:63], v20 offset:32256
	s_nop 0
	v_cndmask_b32_e32 v72, v5, v13, vcc
	ds_read_b128 v[10:13], v20 offset:23040
	v_mfma_f32_16x16x32_bf16 v[2:5], v[64:67], v[34:37], v[30:33]
	ds_read_b128 v[64:67], v20 offset:23104
	s_nop 1
	v_or_b32_e32 v30, 16, v59
	v_cmp_lt_i32_e32 vcc, v68, v30
	ds_read_b128 v[30:33], v20 offset:32320
	s_waitcnt lgkmcnt(3)
	v_mfma_f32_16x16x32_bf16 v[60:63], v[60:63], v[6:9], 0
	v_cndmask_b32_e32 v73, v26, v2, vcc
	v_or_b32_e32 v2, 17, v59
	v_cmp_lt_i32_e32 vcc, v68, v2
	s_waitcnt lgkmcnt(2)
	v_mfma_f32_16x16x32_bf16 v[10:13], v[10:13], v[22:25], 0
	v_or_b32_e32 v2, 18, v59
	v_cndmask_b32_e32 v74, v27, v3, vcc
	v_cmp_lt_i32_e32 vcc, v68, v2
	v_or_b32_e32 v2, 19, v59
	s_waitcnt lgkmcnt(0)
	v_mfma_f32_16x16x32_bf16 v[30:33], v[30:33], v[14:17], v[60:63]
	v_cndmask_b32_e32 v75, v28, v4, vcc
	v_cmp_lt_i32_e32 vcc, v68, v2
	v_or_b32_e32 v26, 32, v59
	ds_read_b128 v[60:63], v20 offset:34560
	v_cndmask_b32_e32 v76, v29, v5, vcc
	v_mfma_f32_16x16x32_bf16 v[2:5], v[64:67], v[34:37], v[10:13]
	v_cmp_lt_i32_e32 vcc, v68, v26
	ds_read_b128 v[26:29], v20 offset:34624
	ds_read_b128 v[64:67], v20 offset:25408
	ds_read_b128 v[10:13], v20 offset:25344
	s_waitcnt lgkmcnt(3)
	v_mfma_f32_16x16x32_bf16 v[60:63], v[60:63], v[6:9], 0
	s_nop 1
	v_cndmask_b32_e32 v77, v30, v2, vcc
	v_or_b32_e32 v2, 33, v59
	v_cmp_lt_i32_e32 vcc, v68, v2
	s_waitcnt lgkmcnt(0)
	v_mfma_f32_16x16x32_bf16 v[10:13], v[10:13], v[22:25], 0
	v_or_b32_e32 v2, 34, v59
	v_cndmask_b32_e32 v78, v31, v3, vcc
	v_cmp_lt_i32_e32 vcc, v68, v2
	v_or_b32_e32 v2, 35, v59
	v_mfma_f32_16x16x32_bf16 v[22:25], v[26:29], v[14:17], v[60:63]
	v_cndmask_b32_e32 v20, v32, v4, vcc
	v_cmp_lt_i32_e32 vcc, v68, v2
	v_lshlrev_b32_e32 v26, 1, v59
	v_or_b32_e32 v30, 48, v59
	v_cndmask_b32_e32 v79, v33, v5, vcc
	v_mfma_f32_16x16x32_bf16 v[2:5], v[64:67], v[34:37], v[10:13]
	v_mad_u32_u24 v60, v54, s98, v26
	v_add_u32_e32 v64, 0x9000, v60
	v_cmp_lt_i32_e32 vcc, v68, v30
	v_add_u32_e32 v65, 0x9800, v60
	v_add_u32_e32 v66, 0xa000, v60
	v_add_u32_e32 v67, 0xa800, v60
	v_cvt_pk_bf16_f32 v10, v69, v70
	v_cvt_pk_bf16_f32 v11, v71, v72
	v_cvt_pk_bf16_f32 v12, v73, v74
	v_cvt_pk_bf16_f32 v13, v75, v76
	ds_read2_b64 v[26:29], v64 offset1:4
	v_cndmask_b32_e32 v22, v22, v2, vcc
	v_or_b32_e32 v2, 49, v59
	ds_read2_b64 v[30:33], v65 offset0:32 offset1:36
	ds_read2_b64 v[34:37], v66 offset0:64 offset1:68
	ds_read2_b64 v[60:63], v67 offset0:96 offset1:100
	v_cmp_lt_i32_e32 vcc, v68, v2
	v_or_b32_e32 v2, 50, v59
	s_waitcnt lgkmcnt(3)
	v_mfma_f32_16x16x32_bf16 v[26:29], v[10:13], v[26:29], 0
	v_cndmask_b32_e32 v23, v23, v3, vcc
	v_cmp_lt_i32_e32 vcc, v68, v2
	v_or_b32_e32 v2, 51, v59
	s_waitcnt lgkmcnt(2)
	v_mfma_f32_16x16x32_bf16 v[30:33], v[10:13], v[30:33], 0
	v_cndmask_b32_e32 v24, v24, v4, vcc
	v_cmp_lt_i32_e32 vcc, v68, v2
	s_waitcnt lgkmcnt(1)
	v_mfma_f32_16x16x32_bf16 v[34:37], v[10:13], v[34:37], 0
	v_cndmask_b32_e32 v25, v25, v5, vcc
	s_waitcnt lgkmcnt(0)
	v_mfma_f32_16x16x32_bf16 v[2:5], v[10:13], v[60:63], 0
	v_cvt_pk_bf16_f32 v10, v77, v78
	v_cvt_pk_bf16_f32 v11, v20, v79
	v_cvt_pk_bf16_f32 v12, v22, v23
	v_cvt_pk_bf16_f32 v13, v24, v25
	ds_read2_b64 v[22:25], v64 offset0:8 offset1:12
	s_waitcnt lgkmcnt(0)
	v_mfma_f32_16x16x32_bf16 v[22:25], v[10:13], v[22:25], v[26:29]
	s_nop 2
	ds_read2_b64 v[26:29], v65 offset0:40 offset1:44
	s_waitcnt lgkmcnt(0)
	v_mfma_f32_16x16x32_bf16 v[26:29], v[10:13], v[26:29], v[30:33]
	s_nop 2
	ds_read2_b64 v[30:33], v66 offset0:72 offset1:76
	s_waitcnt lgkmcnt(0)
	v_mfma_f32_16x16x32_bf16 v[30:33], v[10:13], v[30:33], v[34:37]
	s_nop 2
	ds_read2_b64 v[34:37], v67 offset0:104 offset1:108
	s_waitcnt lgkmcnt(0)
	v_mfma_f32_16x16x32_bf16 v[2:5], v[10:13], v[34:37], v[2:5]
	v_and_b32_e32 v10, 48, v53
	v_mad_u32_u24 v20, v54, s98, v10
	ds_read_b128 v[10:13], v20 offset:46080
	s_waitcnt lgkmcnt(0)
	v_mfma_f32_16x16x32_bf16 v[10:13], v[6:9], v[10:13], v[22:25]
	s_nop 2
	ds_read_b128 v[22:25], v20 offset:48384
	s_waitcnt lgkmcnt(0)
	v_mfma_f32_16x16x32_bf16 v[22:25], v[6:9], v[22:25], v[26:29]
	s_nop 2
	ds_read_b128 v[26:29], v20 offset:50688
	s_waitcnt lgkmcnt(0)
	v_mfma_f32_16x16x32_bf16 v[26:29], v[6:9], v[26:29], v[30:33]
	s_nop 2
	ds_read_b128 v[30:33], v20 offset:52992
	s_waitcnt lgkmcnt(0)
	v_mfma_f32_16x16x32_bf16 v[30:33], v[6:9], v[30:33], v[2:5]
	ds_read_b128 v[6:9], v20 offset:48448
	s_nop 1
	ds_read_b128 v[2:5], v20 offset:46144
	s_waitcnt lgkmcnt(0)
	v_mfma_f32_16x16x32_bf16 v[2:5], v[14:17], v[2:5], v[10:13]
	s_nop 2
	ds_read_b128 v[10:13], v20 offset:50752
	v_mfma_f32_16x16x32_bf16 v[6:9], v[14:17], v[6:9], v[22:25]
	s_nop 2
	ds_read_b128 v[22:25], v20 offset:53056
	s_waitcnt lgkmcnt(1)
	v_mfma_f32_16x16x32_bf16 v[10:13], v[14:17], v[10:13], v[26:29]
	v_and_b32_e32 v20, 64, v159
	v_add_u32_e32 v20, 64, v20
	s_waitcnt lgkmcnt(0)
	v_mfma_f32_16x16x32_bf16 v[14:17], v[14:17], v[22:25], v[30:33]
	v_mov_b32_e32 v22, v2
	s_nop 2
	v_mov_b32_e32 v23, v10
	v_mov_b32_e32 v24, v6
	v_xor_b32_e32 v27, 1, v159
	s_nop 0
	v_mov_b32_e32 v25, v14
	v_pk_add_f32 v[22:23], v[22:23], v[24:25]
	s_nop 0
	v_add_f32_e32 v22, v22, v23
	v_xor_b32_e32 v23, 8, v159
	v_cmp_lt_i32_e32 vcc, v23, v20
	s_nop 1
	v_cndmask_b32_e32 v23, v159, v23, vcc
	v_lshlrev_b32_e32 v32, 2, v23
	s_nop 1
	v_mov_b32_dpp v23, v22 row_ror:8 row_mask:0xf bank_mask:0xf
	s_waitcnt lgkmcnt(0)
	v_add_f32_e32 v22, v22, v23
	v_xor_b32_e32 v23, 4, v159
	v_cmp_lt_i32_e32 vcc, v23, v20
	s_nop 1
	v_cndmask_b32_e32 v23, v159, v23, vcc
	v_lshlrev_b32_e32 v33, 2, v23
	s_nop 1
	v_mov_b32_dpp v23, v22 row_ror:4 row_mask:0xf bank_mask:0xf
	s_waitcnt lgkmcnt(0)
	v_add_f32_e32 v22, v22, v23
	v_xor_b32_e32 v23, 2, v159
	v_cmp_lt_i32_e32 vcc, v23, v20
	s_nop 1
	v_cndmask_b32_e32 v23, v159, v23, vcc
	v_lshlrev_b32_e32 v34, 2, v23
	s_nop 1
	v_mov_b32_dpp v23, v22 row_ror:2 row_mask:0xf bank_mask:0xf
	v_cmp_lt_i32_e32 vcc, v27, v20
	s_waitcnt lgkmcnt(0)
	v_add_f32_e32 v26, v22, v23
	v_mov_b32_e32 v22, v14
	v_mov_b32_e32 v23, v10
	v_mov_b32_e32 v10, v3
	v_mov_b32_e32 v14, v7
	v_pk_add_f32 v[24:25], v[10:11], v[14:15]
	v_cndmask_b32_e32 v20, v159, v27, vcc
	v_add_f32_e32 v10, v24, v25
	s_nop 1
	v_mov_b32_dpp v14, v10 row_ror:8 row_mask:0xf bank_mask:0xf
	v_lshlrev_b32_e32 v20, 2, v20
	s_nop 1
	v_mov_b32_dpp v24, v26 row_ror:1 row_mask:0xf bank_mask:0xf
	v_mov_b32_e32 v25, v6
	s_waitcnt lgkmcnt(1)
	v_add_f32_e32 v10, v10, v14
	s_nop 1
	v_mov_b32_dpp v14, v10 row_ror:4 row_mask:0xf bank_mask:0xf
	s_waitcnt lgkmcnt(1)
	v_add_f32_e32 v24, v26, v24
	s_waitcnt lgkmcnt(0)
	v_add_f32_e32 v14, v10, v14
	s_nop 1
	v_mov_b32_dpp v26, v14 row_ror:2 row_mask:0xf bank_mask:0xf
	v_mul_f32_e32 v10, 0x3c800000, v24
	v_mov_b32_e32 v24, v2
	v_cndmask_b32_e64 v10, 0, v10, s[38:39]
	v_pk_add_f32 v[24:25], v[24:25], v[10:11] op_sel_hi:[1,0] neg_lo:[0,1] neg_hi:[0,1]
	s_waitcnt lgkmcnt(0)
	v_add_f32_e32 v2, v14, v26
	s_nop 1
	v_mov_b32_dpp v6, v2 row_ror:1 row_mask:0xf bank_mask:0xf
	v_pk_add_f32 v[22:23], v[22:23], v[10:11] op_sel_hi:[1,0] neg_lo:[0,1] neg_hi:[0,1]
	v_mov_b32_e32 v10, v15
	v_pk_mul_f32 v[26:27], v[24:25], v[24:25]
	v_pk_mul_f32 v[28:29], v[22:23], v[22:23]
	s_waitcnt lgkmcnt(0)
	v_add_f32_e32 v2, v2, v6
	v_mul_f32_e32 v2, 0x3c800000, v2
	v_cndmask_b32_e64 v2, 0, v2, s[38:39]
	v_mov_b32_e32 v6, v3
	v_pk_add_f32 v[6:7], v[6:7], v[2:3] op_sel_hi:[1,0] neg_lo:[0,1] neg_hi:[0,1]
	v_pk_add_f32 v[10:11], v[10:11], v[2:3] op_sel_hi:[1,0] neg_lo:[0,1] neg_hi:[0,1]
	v_pk_mul_f32 v[30:31], v[6:7], v[6:7]
	v_pk_mul_f32 v[2:3], v[10:11], v[10:11]
	v_mov_b32_e32 v14, v30
	v_mov_b32_e32 v15, v26
	v_mov_b32_e32 v26, v31
	v_pk_add_f32 v[14:15], v[14:15], v[26:27]
	v_mov_b32_e32 v26, v3
	v_mov_b32_e32 v27, v29
	v_pk_add_f32 v[14:15], v[26:27], v[14:15]
	v_mov_b32_e32 v3, v28
	v_pk_add_f32 v[2:3], v[2:3], v[14:15]
	s_nop 1
	v_mov_b32_dpp v15, v3 row_ror:8 row_mask:0xf bank_mask:0xf
	s_nop 1
	v_mov_b32_dpp v14, v2 row_ror:8 row_mask:0xf bank_mask:0xf
	s_waitcnt vmcnt(15)
	v_lshlrev_b32_e32 v28, 16, v58
	s_waitcnt vmcnt(11)
	v_lshlrev_b32_e32 v30, 16, v56
	s_waitcnt vmcnt(8)
	v_lshlrev_b32_e32 v31, 16, v57
	s_waitcnt lgkmcnt(0)
	v_pk_add_f32 v[2:3], v[2:3], v[14:15]
	s_nop 1
	v_mov_b32_dpp v15, v3 row_ror:4 row_mask:0xf bank_mask:0xf
	s_nop 1
	v_mov_b32_dpp v14, v2 row_ror:4 row_mask:0xf bank_mask:0xf
	s_waitcnt lgkmcnt(0)
	v_pk_add_f32 v[2:3], v[2:3], v[14:15]
	s_nop 1
	v_mov_b32_dpp v15, v3 row_ror:2 row_mask:0xf bank_mask:0xf
	s_nop 1
	v_mov_b32_dpp v14, v2 row_ror:2 row_mask:0xf bank_mask:0xf
	s_waitcnt lgkmcnt(0)
	v_pk_add_f32 v[14:15], v[2:3], v[14:15]
	s_nop 1
	v_mov_b32_dpp v27, v15 row_ror:1 row_mask:0xf bank_mask:0xf
	s_nop 1
	v_mov_b32_dpp v26, v14 row_ror:1 row_mask:0xf bank_mask:0xf
	v_lshl_add_u32 v245, v18, 6, v0
	v_add_u32_e32 v246, 0x100000, v245
	s_waitcnt lgkmcnt(0)
	v_pk_add_f32 v[14:15], v[14:15], v[26:27]
	v_mov_b64_e32 v[26:27], s[34:35]
	s_mov_b32 s34, 0x3c800000
	v_pk_fma_f32 v[14:15], v[14:15], s[34:35], v[26:27] op_sel_hi:[1,0,0]
	s_nop 0
	v_mul_f32_e32 v29, 0x4b800000, v15
	v_cmp_gt_f32_e32 vcc, s84, v15
	s_nop 1
	v_cndmask_b32_e32 v15, v15, v29, vcc
	v_rsq_f32_e32 v15, v15
	v_lshlrev_b32_e32 v29, 16, v55
	v_mul_f32_e32 v35, 0x45800000, v15
	v_cndmask_b32_e32 v15, v15, v35, vcc
	v_mul_f32_e32 v24, v24, v15
	v_mul_f32_e32 v24, v40, v24
	v_mul_f32_e32 v24, v24, v28
	v_cvt_pk_bf16_f32 v24, v24, s0
	global_store_short v245, v24, s[6:7]
	v_mul_f32_e32 v24, v25, v15
	v_mul_f32_e32 v23, v23, v15
	v_mul_f32_e32 v15, v22, v15
	v_mul_f32_e32 v24, v39, v24
	v_mul_f32_e32 v23, v38, v23
	v_mul_f32_e32 v15, v21, v15
	v_mul_f32_e32 v24, v24, v29
	v_mul_f32_e32 v23, v23, v30
	v_mul_f32_e32 v15, v15, v31
	v_cvt_pk_bf16_f32 v24, v24, s0
	v_cvt_pk_bf16_f32 v23, v23, s0
	v_mul_f32_e32 v22, 0x4b800000, v14
	v_cmp_gt_f32_e32 vcc, s84, v14
	v_cvt_pk_bf16_f32 v15, v15, s0
	global_store_short v245, v24, s[6:7] offset:32
	global_store_short v246, v23, s[6:7]
	v_cndmask_b32_e32 v14, v14, v22, vcc
	global_store_short v246, v15, s[6:7] offset:32
	v_mov_b32_e32 v18, v4
	v_mov_b32_e32 v19, v12
	v_mov_b32_e32 v22, v8
	v_mov_b32_e32 v23, v16
	v_pk_add_f32 v[18:19], v[18:19], v[22:23]
	v_rsq_f32_e32 v14, v14
	v_add_f32_e32 v18, v18, v19
	s_nop 1
	v_mov_b32_dpp v19, v18 row_ror:8 row_mask:0xf bank_mask:0xf
	v_lshlrev_b32_e32 v24, 16, v52
	v_mul_f32_e32 v15, 0x45800000, v14
	v_cndmask_b32_e32 v30, v14, v15, vcc
	v_mul_f32_e32 v6, v6, v30
	s_waitcnt lgkmcnt(0)
	v_add_f32_e32 v18, v18, v19
	s_nop 1
	v_mov_b32_dpp v19, v18 row_ror:4 row_mask:0xf bank_mask:0xf
	v_mul_f32_e32 v6, v40, v6
	v_mul_f32_e32 v6, v6, v24
	v_cvt_pk_bf16_f32 v6, v6, s0
	global_store_short v245, v6, s[6:7] offset:64
	v_mul_f32_e32 v23, v7, v30
	v_mov_b32_e32 v6, v16
	v_mov_b32_e32 v7, v12
	v_mov_b32_e32 v12, v5
	v_mov_b32_e32 v16, v9
	s_waitcnt lgkmcnt(0)
	v_add_f32_e32 v24, v18, v19
	v_pk_add_f32 v[18:19], v[12:13], v[16:17]
	s_nop 1
	v_mov_b32_dpp v25, v24 row_ror:2 row_mask:0xf bank_mask:0xf
	v_add_f32_e32 v12, v18, v19
	s_nop 1
	v_mov_b32_dpp v16, v12 row_ror:8 row_mask:0xf bank_mask:0xf
	v_lshlrev_b32_e32 v22, 16, v51
	v_mul_f32_e32 v18, v39, v23
	s_waitcnt lgkmcnt(1)
	v_add_f32_e32 v19, v24, v25
	v_mul_f32_e32 v18, v18, v22
	s_waitcnt lgkmcnt(0)
	v_add_f32_e32 v12, v12, v16
	s_nop 1
	v_mov_b32_dpp v16, v12 row_ror:4 row_mask:0xf bank_mask:0xf
	s_nop 1
	v_mov_b32_dpp v22, v19 row_ror:1 row_mask:0xf bank_mask:0xf
	v_cvt_pk_bf16_f32 v18, v18, s0
	global_store_short v245, v18, s[6:7] offset:96
	v_mul_f32_e32 v11, v11, v30
	s_waitcnt lgkmcnt(1)
	v_add_f32_e32 v16, v12, v16
	s_waitcnt lgkmcnt(0)
	v_add_f32_e32 v18, v19, v22
	s_nop 1
	v_mov_b32_dpp v22, v16 row_ror:2 row_mask:0xf bank_mask:0xf
	v_mul_f32_e32 v12, 0x3c800000, v18
	v_mov_b32_e32 v18, v4
	v_mov_b32_e32 v19, v8
	v_cndmask_b32_e64 v12, 0, v12, s[38:39]
	s_waitcnt lgkmcnt(0)
	v_add_f32_e32 v4, v16, v22
	s_nop 1
	v_mov_b32_dpp v8, v4 row_ror:1 row_mask:0xf bank_mask:0xf
	v_pk_add_f32 v[18:19], v[18:19], v[12:13] op_sel_hi:[1,0] neg_lo:[0,1] neg_hi:[0,1]
	v_pk_add_f32 v[6:7], v[6:7], v[12:13] op_sel_hi:[1,0] neg_lo:[0,1] neg_hi:[0,1]
	v_mov_b32_e32 v12, v17
	v_pk_mul_f32 v[22:23], v[18:19], v[18:19]
	s_waitcnt lgkmcnt(0)
	v_add_f32_e32 v4, v4, v8
	v_mul_f32_e32 v4, 0x3c800000, v4
	v_cndmask_b32_e64 v4, 0, v4, s[38:39]
	v_mov_b32_e32 v8, v5
	v_pk_add_f32 v[8:9], v[8:9], v[4:5] op_sel_hi:[1,0] neg_lo:[0,1] neg_hi:[0,1]
	v_pk_add_f32 v[4:5], v[12:13], v[4:5] op_sel_hi:[1,0] neg_lo:[0,1] neg_hi:[0,1]
	v_pk_mul_f32 v[28:29], v[8:9], v[8:9]
	v_pk_mul_f32 v[24:25], v[6:7], v[6:7]
	v_pk_mul_f32 v[12:13], v[4:5], v[4:5]
	v_mov_b32_e32 v16, v28
	v_mov_b32_e32 v17, v22
	v_mov_b32_e32 v22, v29
	v_pk_add_f32 v[16:17], v[16:17], v[22:23]
	v_mov_b32_e32 v22, v13
	v_mov_b32_e32 v23, v25
	v_pk_add_f32 v[16:17], v[22:23], v[16:17]
	v_mov_b32_e32 v13, v24
	v_pk_add_f32 v[12:13], v[12:13], v[16:17]
	s_nop 1
	v_mov_b32_dpp v17, v13 row_ror:8 row_mask:0xf bank_mask:0xf
	s_nop 1
	v_mov_b32_dpp v16, v12 row_ror:8 row_mask:0xf bank_mask:0xf
	v_lshlrev_b32_e32 v31, 16, v50
	v_mul_f32_e32 v11, v38, v11
	v_mul_f32_e32 v11, v11, v31
	v_cvt_pk_bf16_f32 v11, v11, s0
	s_waitcnt lgkmcnt(0)
	v_pk_add_f32 v[12:13], v[12:13], v[16:17]
	s_nop 1
	v_mov_b32_dpp v17, v13 row_ror:4 row_mask:0xf bank_mask:0xf
	s_nop 1
	v_mov_b32_dpp v16, v12 row_ror:4 row_mask:0xf bank_mask:0xf
	v_mul_f32_e32 v10, v10, v30
	global_store_short v246, v11, s[6:7] offset:64
	v_mul_f32_e32 v23, v21, v10
	v_lshlrev_b32_e32 v22, 16, v49
	s_waitcnt lgkmcnt(0)
	v_pk_add_f32 v[10:11], v[12:13], v[16:17]
	s_nop 1
	v_mov_b32_dpp v13, v11 row_ror:2 row_mask:0xf bank_mask:0xf
	s_nop 1
	v_mov_b32_dpp v12, v10 row_ror:2 row_mask:0xf bank_mask:0xf
	v_mul_f32_e32 v16, v23, v22
	v_cvt_pk_bf16_f32 v16, v16, s0
	global_store_short v246, v16, s[6:7] offset:96
	s_waitcnt lgkmcnt(0)
	v_pk_add_f32 v[10:11], v[10:11], v[12:13]
	s_nop 1
	v_mov_b32_dpp v13, v11 row_ror:1 row_mask:0xf bank_mask:0xf
	s_nop 1
	v_mov_b32_dpp v12, v10 row_ror:1 row_mask:0xf bank_mask:0xf
	s_waitcnt vmcnt(8)
	v_lshlrev_b32_e32 v17, 16, v47
	s_waitcnt lgkmcnt(0)
	v_pk_add_f32 v[10:11], v[10:11], v[12:13]
	v_lshlrev_b32_e32 v13, 16, v46
	v_pk_fma_f32 v[10:11], v[10:11], s[34:35], v[26:27] op_sel_hi:[1,0,0]
	v_mul_f32_e32 v12, 0x4b800000, v11
	v_cmp_gt_f32_e32 vcc, s84, v11
	v_cndmask_b32_e32 v11, v11, v12, vcc
	v_rsq_f32_e32 v11, v11
	v_lshlrev_b32_e32 v0, 16, v43
	v_lshlrev_b32_e32 v16, 16, v48
	v_lshlrev_b32_e32 v12, 16, v45
	v_mul_f32_e32 v20, 0x45800000, v11
	v_cndmask_b32_e32 v11, v11, v20, vcc
	v_mul_f32_e32 v7, v7, v11
	v_mul_f32_e32 v7, v38, v7
	v_mul_f32_e32 v7, v7, v13
	v_cvt_pk_bf16_f32 v7, v7, s0
	global_store_short v246, v7, s[6:7] offset:128
	v_mul_f32_e32 v7, 0x4b800000, v10
	v_cmp_gt_f32_e32 vcc, s84, v10
	v_mul_f32_e32 v6, v6, v11
	v_mul_f32_e32 v6, v21, v6
	v_cndmask_b32_e32 v7, v10, v7, vcc
	v_rsq_f32_e32 v7, v7
	v_mul_f32_e32 v6, v6, v17
	v_cvt_pk_bf16_f32 v6, v6, s0
	global_store_short v246, v6, s[6:7] offset:160
	v_mul_f32_e32 v6, 0x45800000, v7
	v_cndmask_b32_e32 v6, v7, v6, vcc
	v_mul_f32_e32 v8, v8, v6
	v_lshlrev_b32_e32 v7, 16, v44
	v_mul_f32_e32 v8, v40, v8
	v_mul_f32_e32 v7, v8, v7
	v_cvt_pk_bf16_f32 v7, v7, s0
	global_store_short v245, v7, s[6:7] offset:192
	v_mul_f32_e32 v7, v9, v6
	v_mul_f32_e32 v7, v39, v7
	v_mul_f32_e32 v18, v18, v11
	v_mul_f32_e32 v0, v7, v0
	v_mul_f32_e32 v18, v40, v18
	v_cvt_pk_bf16_f32 v0, v0, s0
	v_mul_f32_e32 v5, v5, v6
	v_mul_f32_e32 v16, v18, v16
	global_store_short v245, v0, s[6:7] offset:224
	v_lshlrev_b32_e32 v0, 16, v42
	v_mul_f32_e32 v5, v38, v5
	v_cvt_pk_bf16_f32 v16, v16, s0
	v_mul_f32_e32 v0, v5, v0
	global_store_short v245, v16, s[6:7] offset:128
	v_mul_f32_e32 v16, v19, v11
	v_cvt_pk_bf16_f32 v0, v0, s0
	v_mul_f32_e32 v4, v4, v6
	v_mul_f32_e32 v16, v39, v16
	global_store_short v246, v0, s[6:7] offset:192
	v_lshlrev_b32_e32 v0, 16, v41
	v_mul_f32_e32 v4, v21, v4
	v_mul_f32_e32 v12, v16, v12
	v_mul_f32_e32 v0, v4, v0
	v_cvt_pk_bf16_f32 v12, v12, s0
	v_cvt_pk_bf16_f32 v0, v0, s0
	global_store_short v245, v12, s[6:7] offset:160
	global_store_short v246, v0, s[6:7] offset:224
	s_branch .LBB0_180

.Lxb_full:
	v_readlane_b32 s6, v244, 46
	v_readlane_b32 s7, v244, 47
	s_sub_i32 s24, s23, s3
	s_mov_b32 s3, 0
	s_waitcnt vmcnt(0)
	global_atomic_add v1, v158, s[18:19] offset:128
	s_nop 1
